# final modulate phase: all per-row loads (scale/shift/gate/delta) prefetched one row ahead into shadow registers, single vmcnt at loop top
# speedup vs baseline: 1.0515x; 1.0043x over previous
.LBB0_11:
	v_writelane_b32 v240, s84, 7
	v_mov_b32_e32 v182, v222
	s_mov_b32 s27, s84
	v_writelane_b32 v240, s85, 8
	v_writelane_b32 v240, s86, 9
	v_writelane_b32 v240, s87, 10
	s_mov_b64 s[0:1], -1
	s_mov_b64 s[20:21], 0
	s_cmp_lt_i32 s84, 7
	s_mov_b64 s[66:67], 0
	s_mov_b64 s[68:69], 0
	v_writelane_b32 v240, s27, 11
	s_cbranch_scc1 .LBB0_92
	s_cmp_gt_i32 s27, 10
	s_cbranch_scc0 .LBB0_21
	s_mov_b64 s[42:43], 0
	s_cmp_gt_i32 s27, 12
	s_cbranch_scc0 .LBB0_28
	s_cmp_gt_i32 s27, 14
	s_cbranch_scc0 .LBB0_23
	s_cmp_eq_u32 s27, 15
	s_mov_b64 s[68:69], -1
	s_cbranch_scc0 .LBB0_22
	v_ashrrev_i32_e32 v0, 6, v182
	v_readlane_b32 s0, v243, 4
	s_nop 1
	v_add_u32_e32 v96, s0, v0
	v_cmp_gt_i32_e32 vcc, s98, v96
	s_and_saveexec_b64 s[28:29], vcc
	s_cbranch_execz .LBB0_26
	v_readlane_b32 s4, v241, 32
	v_ashrrev_i32_e32 v97, 31, v96
	v_lshlrev_b32_e32 v0, 4, v182
	v_readlane_b32 s18, v241, 46
	v_readlane_b32 s19, v241, 47
	s_waitcnt vmcnt(0)
	v_lshlrev_b64 v[18:19], 12, v[96:97]
	v_and_b32_e32 v16, 0x3f0, v0
	v_mov_b32_e32 v17, v180
	v_lshl_add_u64 v[98:99], s[18:19], 0, v[18:19]
	v_readlane_b32 s16, v241, 44
	v_readlane_b32 s17, v241, 45
	v_lshl_add_u64 v[18:19], v[98:99], 0, v[16:17]
	s_nop 3
	global_load_dwordx4 v[0:3], v16, s[16:17]
	global_load_dwordx4 v[4:7], v16, s[16:17] offset:1024
	global_load_dwordx4 v[8:11], v16, s[16:17] offset:2048
	global_load_dwordx4 v[12:15], v16, s[16:17] offset:3072
	global_load_dwordx4 v[52:55], v[18:19], off
	global_load_dwordx4 v[40:43], v[18:19], off offset:1024
	global_load_dwordx4 v[36:39], v[18:19], off offset:2048
	global_load_dwordx4 v[32:35], v[18:19], off offset:3072
	s_load_dword s0, s[24:25], 0x0
	v_cmp_lt_i32_e32 vcc, v229, v228
	v_and_b32_e32 v18, 63, v182
	v_lshlrev_b32_e32 v106, 4, v18
	v_mov_b32_e32 v107, v180
	s_waitcnt lgkmcnt(0)
	s_lshl_b32 s34, s0, 3
	v_readlane_b32 s0, v243, 29
	v_readlane_b32 s1, v243, 30
	s_ashr_i32 s35, s34, 31
	s_lshl_b64 s[36:37], s[34:35], 12
	v_lshl_add_u64 v[100:101], s[0:1], 0, v[16:17]
	v_readlane_b32 s0, v243, 2
	v_readlane_b32 s1, v243, 3
	s_lshl_b64 s[38:39], s[34:35], 11
	s_mov_b64 s[40:41], 0
	v_lshl_add_u64 v[102:103], s[0:1], 0, v[16:17]
	v_readlane_b32 s0, v243, 27
	v_readlane_b32 s1, v243, 28
	v_readlane_b32 s5, v241, 33
	v_readlane_b32 s6, v241, 34
	v_lshl_add_u64 v[104:105], s[0:1], 0, v[16:17]
	v_cndmask_b32_e32 v16, v227, v229, vcc
	v_cmp_lt_i32_e32 vcc, v230, v228
	v_lshlrev_b32_e32 v120, 2, v16
	v_readlane_b32 s7, v241, 35
	v_cndmask_b32_e32 v16, v227, v230, vcc
	v_cmp_lt_i32_e32 vcc, v231, v228
	v_lshlrev_b32_e32 v121, 2, v16
	v_readlane_b32 s8, v241, 36
	v_cndmask_b32_e32 v16, v227, v231, vcc
	v_cmp_lt_i32_e32 vcc, v232, v228
	v_lshlrev_b32_e32 v122, 2, v16
	v_readlane_b32 s9, v241, 37
	v_cndmask_b32_e32 v16, v227, v232, vcc
	v_cmp_lt_i32_e32 vcc, v233, v228
	v_lshlrev_b32_e32 v123, 2, v16
	v_readlane_b32 s10, v241, 38
	v_cndmask_b32_e32 v16, v227, v233, vcc
	v_cmp_lt_i32_e32 vcc, v234, v228
	v_lshlrev_b32_e32 v124, 2, v16
	v_readlane_b32 s11, v241, 39
	v_cndmask_b32_e32 v16, v227, v234, vcc
	v_lshlrev_b32_e32 v125, 2, v16
	v_add_u32_e32 v16, s34, v96
	v_ashrrev_i32_e32 v17, 31, v16
	v_lshlrev_b64 v[16:17], 12, v[16:17]
	v_lshl_add_u64 v[108:109], s[18:19], 0, v[16:17]
	v_lshlrev_b64 v[16:17], 11, v[96:97]
	v_lshl_or_b32 v16, v18, 3, v16
	v_lshl_add_u64 v[110:111], s[44:45], 0, v[16:17]
	v_readlane_b32 s12, v241, 40
	v_readlane_b32 s13, v241, 41
	v_readlane_b32 s14, v241, 42
	v_readlane_b32 s15, v241, 43
	v_ashrrev_i32_e32 v44, 13, v96
	v_ashrrev_i32_e32 v45, 31, v44
	v_lshlrev_b64 v[46:47], 13, v[44:45]
	v_mul_hi_i32_i24_e32 v45, 0x9000, v44
	v_mul_i32_i24_e32 v44, 0x9000, v44
	v_lshl_add_u64 v[48:49], v[100:101], 0, v[46:47]
	v_lshl_add_u64 v[46:47], v[102:103], 0, v[46:47]
	v_lshl_add_u64 v[80:81], v[104:105], 0, v[44:45]
	global_load_dwordx4 v[72:75], v[48:49], off
	global_load_dwordx4 v[68:71], v[48:49], off offset:1024
	global_load_dwordx4 v[76:79], v[46:47], off
	global_load_dwordx4 v[64:67], v[46:47], off offset:1024
	global_load_dwordx4 v[92:95], v[80:81], off
	global_load_dwordx4 v[88:91], v[80:81], off offset:1024
	global_load_dwordx4 v[56:59], v[48:49], off offset:2048
	s_nop 0
	global_load_dwordx4 v[48:51], v[48:49], off offset:3072
	s_nop 0
	global_load_dwordx4 v[60:63], v[46:47], off offset:2048
	s_nop 0
	global_load_dwordx4 v[44:47], v[46:47], off offset:3072
	s_nop 0
	global_load_dwordx2 v[118:119], v[110:111], off
	global_load_dwordx2 v[116:117], v[110:111], off offset:512
	global_load_dwordx2 v[114:115], v[110:111], off offset:1024
	global_load_dwordx2 v[112:113], v[110:111], off offset:1536
	global_load_dwordx4 v[84:87], v[80:81], off offset:2048
	s_nop 0
	global_load_dwordx4 v[80:83], v[80:81], off offset:3072
	s_waitcnt vmcnt(0)
	s_branch .Lp15_entry
.LBB0_18:
	s_or_b64 exec, exec, s[64:65]
	v_pk_mul_f32 v[92:93], v[92:93], 0.5 op_sel_hi:[1,0]
	v_lshlrev_b32_e32 v126, 16, v118
	v_and_b32_e32 v127, 0xffff0000, v118
	v_pk_fma_f32 v[52:53], v[92:93], v[126:127], v[52:53]
	v_pk_mul_f32 v[88:89], v[88:89], 0.5 op_sel_hi:[1,0]
	v_lshlrev_b32_e32 v92, 16, v116
	v_and_b32_e32 v93, 0xffff0000, v116
	v_pk_mul_f32 v[94:95], v[94:95], 0.5 op_sel_hi:[1,0]
	v_lshlrev_b32_e32 v118, 16, v119
	v_and_b32_e32 v119, 0xffff0000, v119
	v_pk_fma_f32 v[40:41], v[88:89], v[92:93], v[40:41]
	v_pk_fma_f32 v[54:55], v[94:95], v[118:119], v[54:55]
	v_mul_f32_e32 v97, v53, v53
	v_pk_mul_f32 v[90:91], v[90:91], 0.5 op_sel_hi:[1,0]
	v_lshlrev_b32_e32 v94, 16, v117
	v_and_b32_e32 v95, 0xffff0000, v117
	v_mul_f32_e32 v88, v41, v41
	v_fmac_f32_e32 v97, v52, v52
	v_pk_fma_f32 v[42:43], v[90:91], v[94:95], v[42:43]
	v_fmac_f32_e32 v88, v40, v40
	v_fmac_f32_e32 v97, v54, v54
	v_fmac_f32_e32 v88, v42, v42
	v_fmac_f32_e32 v97, v55, v55
	v_fmac_f32_e32 v88, v43, v43
	v_add_f32_e32 v92, v97, v88
	v_pk_mul_f32 v[84:85], v[84:85], 0.5 op_sel_hi:[1,0]
	v_lshlrev_b32_e32 v88, 16, v114
	v_and_b32_e32 v89, 0xffff0000, v114
	v_pk_mul_f32 v[86:87], v[86:87], 0.5 op_sel_hi:[1,0]
	v_lshlrev_b32_e32 v90, 16, v115
	v_and_b32_e32 v91, 0xffff0000, v115
	v_pk_fma_f32 v[36:37], v[84:85], v[88:89], v[36:37]
	v_pk_mul_f32 v[80:81], v[80:81], 0.5 op_sel_hi:[1,0]
	v_lshlrev_b32_e32 v84, 16, v112
	v_and_b32_e32 v85, 0xffff0000, v112
	v_pk_fma_f32 v[38:39], v[86:87], v[90:91], v[38:39]
	v_pk_mul_f32 v[82:83], v[82:83], 0.5 op_sel_hi:[1,0]
	v_lshlrev_b32_e32 v86, 16, v113
	v_and_b32_e32 v87, 0xffff0000, v113
	v_pk_fma_f32 v[80:81], v[80:81], v[84:85], v[32:33]
	v_pk_fma_f32 v[82:83], v[82:83], v[86:87], v[34:35]
	v_mov_b32_e32 v34, v37
	v_mov_b32_e32 v35, v81
	v_mov_b32_e32 v32, v36
	v_mov_b32_e32 v33, v80
	v_pk_mul_f32 v[34:35], v[34:35], v[34:35]
	v_lshl_add_u64 v[86:87], v[98:99], 0, v[106:107]
	v_pk_fma_f32 v[32:33], v[32:33], v[32:33], v[34:35]
	v_mov_b32_e32 v34, v38
	v_mov_b32_e32 v35, v82
	v_pk_fma_f32 v[32:33], v[34:35], v[34:35], v[32:33]
	v_mov_b32_e32 v34, v39
	v_mov_b32_e32 v35, v83
	v_pk_fma_f32 v[32:33], v[34:35], v[34:35], v[32:33]
	s_and_b64 s[0:1], exec, vcc
	v_add_f32_e32 v32, v92, v32
	v_add_f32_e32 v32, v32, v33
	ds_bpermute_b32 v33, v120, v32
	s_or_b64 s[40:41], s[0:1], s[40:41]
	v_lshl_add_u64 v[108:109], v[108:109], 0, s[36:37]
	v_lshl_add_u64 v[98:99], v[98:99], 0, s[36:37]
	s_waitcnt lgkmcnt(0)
	v_add_f32_e32 v32, v32, v33
	ds_bpermute_b32 v33, v121, v32
	s_waitcnt lgkmcnt(0)
	v_add_f32_e32 v32, v32, v33
	ds_bpermute_b32 v33, v122, v32
	s_waitcnt lgkmcnt(0)
	v_add_f32_e32 v32, v32, v33
	ds_bpermute_b32 v33, v123, v32
	s_waitcnt lgkmcnt(0)
	v_add_f32_e32 v32, v32, v33
	ds_bpermute_b32 v33, v124, v32
	s_waitcnt lgkmcnt(0)
	v_add_f32_e32 v32, v32, v33
	ds_bpermute_b32 v33, v125, v32
	s_waitcnt lgkmcnt(0)
	v_add_f32_e32 v32, v32, v33
	v_fmamk_f32 v32, v32, 0x3a800000, v224
	v_rsq_f32_e32 v84, v32
	s_nop 0
	v_pk_mul_f32 v[32:33], v[54:55], v[84:85] op_sel_hi:[1,0]
	v_pk_mul_f32 v[34:35], v[52:53], v[84:85] op_sel_hi:[1,0]
	v_pk_mul_f32 v[32:33], v[2:3], v[32:33]
	v_pk_mul_f32 v[52:53], v[0:1], v[34:35]
	v_pk_add_f32 v[34:35], v[74:75], 1.0 op_sel_hi:[1,0]
	v_pk_add_f32 v[54:55], v[72:73], 1.0 op_sel_hi:[1,0]
	v_pk_fma_f32 v[34:35], v[34:35], v[32:33], v[78:79]
	v_pk_fma_f32 v[32:33], v[54:55], v[52:53], v[76:77]
	global_store_dwordx4 v[86:87], v[32:35], off
	s_nop 1
	v_pk_mul_f32 v[32:33], v[42:43], v[84:85] op_sel_hi:[1,0]
	v_pk_mul_f32 v[34:35], v[40:41], v[84:85] op_sel_hi:[1,0]
	v_pk_mul_f32 v[32:33], v[6:7], v[32:33]
	v_pk_mul_f32 v[40:41], v[4:5], v[34:35]
	v_pk_add_f32 v[34:35], v[70:71], 1.0 op_sel_hi:[1,0]
	v_pk_add_f32 v[42:43], v[68:69], 1.0 op_sel_hi:[1,0]
	v_pk_fma_f32 v[34:35], v[34:35], v[32:33], v[66:67]
	v_pk_fma_f32 v[32:33], v[42:43], v[40:41], v[64:65]
	global_store_dwordx4 v[86:87], v[32:35], off offset:1024
	s_nop 1
	v_pk_mul_f32 v[32:33], v[38:39], v[84:85] op_sel_hi:[1,0]
	v_pk_mul_f32 v[34:35], v[36:37], v[84:85] op_sel_hi:[1,0]
	v_pk_mul_f32 v[32:33], v[10:11], v[32:33]
	v_pk_mul_f32 v[36:37], v[8:9], v[34:35]
	v_pk_add_f32 v[34:35], v[58:59], 1.0 op_sel_hi:[1,0]
	v_pk_add_f32 v[38:39], v[56:57], 1.0 op_sel_hi:[1,0]
	v_pk_fma_f32 v[34:35], v[34:35], v[32:33], v[62:63]
	v_pk_fma_f32 v[32:33], v[38:39], v[36:37], v[60:61]
	global_store_dwordx4 v[86:87], v[32:35], off offset:2048
	s_nop 1
	v_pk_add_f32 v[38:39], v[48:49], 1.0 op_sel_hi:[1,0]
	v_pk_mul_f32 v[32:33], v[82:83], v[84:85] op_sel_hi:[1,0]
	v_pk_mul_f32 v[34:35], v[80:81], v[84:85] op_sel_hi:[1,0]
	v_pk_mul_f32 v[32:33], v[14:15], v[32:33]
	v_pk_mul_f32 v[36:37], v[12:13], v[34:35]
	v_pk_add_f32 v[34:35], v[50:51], 1.0 op_sel_hi:[1,0]
	v_pk_fma_f32 v[34:35], v[34:35], v[32:33], v[46:47]
	v_pk_fma_f32 v[32:33], v[38:39], v[36:37], v[44:45]
	global_store_dwordx4 v[86:87], v[32:35], off offset:3072
	s_nop 1
	s_andn2_b64 exec, exec, s[40:41]
	s_cbranch_execz .LBB0_26
.LBB0_19:
	s_waitcnt vmcnt(4)
	v_mov_b64_e32 v[44:45], v[128:129]
	v_mov_b64_e32 v[46:47], v[130:131]
	v_mov_b64_e32 v[48:49], v[132:133]
	v_mov_b64_e32 v[50:51], v[134:135]
	v_mov_b64_e32 v[56:57], v[136:137]
	v_mov_b64_e32 v[58:59], v[138:139]
	v_mov_b64_e32 v[60:61], v[140:141]
	v_mov_b64_e32 v[62:63], v[142:143]
	v_mov_b64_e32 v[64:65], v[144:145]
	v_mov_b64_e32 v[66:67], v[146:147]
	v_mov_b64_e32 v[68:69], v[148:149]
	v_mov_b64_e32 v[70:71], v[150:151]
	v_mov_b64_e32 v[72:73], v[152:153]
	v_mov_b64_e32 v[74:75], v[154:155]
	v_mov_b64_e32 v[76:77], v[156:157]
	v_mov_b64_e32 v[78:79], v[158:159]
	v_mov_b64_e32 v[80:81], v[160:161]
	v_mov_b64_e32 v[82:83], v[162:163]
	v_mov_b64_e32 v[84:85], v[164:165]
	v_mov_b64_e32 v[86:87], v[166:167]
	v_mov_b64_e32 v[88:89], v[168:169]
	v_mov_b64_e32 v[90:91], v[170:171]
	v_mov_b64_e32 v[92:93], v[172:173]
	v_mov_b64_e32 v[94:95], v[174:175]
	v_mov_b64_e32 v[112:113], v[176:177]
	v_mov_b64_e32 v[114:115], v[178:179]
	v_mov_b64_e32 v[116:117], v[184:185]
	v_mov_b64_e32 v[118:119], v[186:187]
	v_mov_b64_e32 v[52:53], v[16:17]
	v_mov_b64_e32 v[54:55], v[18:19]
	v_mov_b64_e32 v[40:41], v[20:21]
	v_mov_b64_e32 v[42:43], v[22:23]
	v_mov_b64_e32 v[36:37], v[24:25]
	v_mov_b64_e32 v[38:39], v[26:27]
	v_mov_b64_e32 v[32:33], v[28:29]
	v_mov_b64_e32 v[34:35], v[30:31]
.Lp15_entry:
	v_add_u32_e32 v96, s34, v96
	v_lshl_add_u64 v[110:111], v[110:111], 0, s[38:39]
	v_ashrrev_i32_e32 v188, 13, v96
	v_ashrrev_i32_e32 v189, 31, v188
	v_lshlrev_b64 v[190:191], 13, v[188:189]
	v_mul_hi_i32_i24_e32 v189, 0x9000, v188
	v_mul_i32_i24_e32 v188, 0x9000, v188
	v_lshl_add_u64 v[192:193], v[100:101], 0, v[190:191]
	v_lshl_add_u64 v[190:191], v[102:103], 0, v[190:191]
	v_lshl_add_u64 v[194:195], v[104:105], 0, v[188:189]
	global_load_dwordx4 v[152:155], v[192:193], off
	global_load_dwordx4 v[148:151], v[192:193], off offset:1024
	global_load_dwordx4 v[156:159], v[190:191], off
	global_load_dwordx4 v[144:147], v[190:191], off offset:1024
	global_load_dwordx4 v[172:175], v[194:195], off
	global_load_dwordx4 v[168:171], v[194:195], off offset:1024
	global_load_dwordx4 v[136:139], v[192:193], off offset:2048
	s_nop 0
	global_load_dwordx4 v[132:135], v[192:193], off offset:3072
	s_nop 0
	global_load_dwordx4 v[140:143], v[190:191], off offset:2048
	s_nop 0
	global_load_dwordx4 v[128:131], v[190:191], off offset:3072
	s_nop 0
	global_load_dwordx2 v[186:187], v[110:111], off
	global_load_dwordx2 v[184:185], v[110:111], off offset:512
	global_load_dwordx2 v[178:179], v[110:111], off offset:1024
	global_load_dwordx2 v[176:177], v[110:111], off offset:1536
	global_load_dwordx4 v[164:167], v[194:195], off offset:2048
	s_nop 0
	global_load_dwordx4 v[160:163], v[194:195], off offset:3072
	v_cmp_gt_i32_e64 s[0:1], s98, v96
	v_cmp_lt_i32_e32 vcc, s99, v96
	s_and_saveexec_b64 s[64:65], s[0:1]
	s_cbranch_execz .LBB0_18
	v_lshl_add_u64 v[28:29], v[108:109], 0, v[106:107]
	global_load_dwordx4 v[16:19], v[28:29], off
	global_load_dwordx4 v[20:23], v[28:29], off offset:1024
	global_load_dwordx4 v[24:27], v[28:29], off offset:2048
	s_nop 0
	global_load_dwordx4 v[28:31], v[28:29], off offset:3072
	s_branch .LBB0_18
